# retention core: state-update MFMAs compute S instead of S^T (operands swapped) so the bf16 state image is written with 8 ds_write_b64 per chunk instead of 32 ds_write_b16 (LDS layout and readers uncha
# speedup vs baseline: 1.0038x; 1.0038x over previous
; template <int DK, int DVS, bool RET> ...
;     ...
;     unsigned aQD = (unsigned)(uintptr_t)(LAS unsigned char*)lds, aKD = aQD + 64 * LK * 2, aSTB = aKD + 64 * LK * 2, aVI = aSTB + DVS * LK * 2,
;              aAT = aVI + 64 * LV * 2, aEL = aAT + 64 * LS * 2, aTOT = aEL + DK * 4;
;     asm volatile("" : "+s"(aQD), "+s"(aVI), "+s"(aAT), "+s"(aEL), "+s"(aTOT), "+s"(aKD), "+s"(aSTB));
;     LAS bf16_t* QD = (LAS bf16_t*)(uintptr_t)aQD; LAS bf16_t* VI = (LAS bf16_t*)(uintptr_t)aVI; LAS bf16_t* AT = (LAS bf16_t*)(uintptr_t)aAT;
;     LAS float* EL = (LAS float*)(uintptr_t)aEL; LAS float* TOT = (LAS float*)(uintptr_t)aTOT;
;     LAS bf16_t* KD = (LAS bf16_t*)(uintptr_t)aKD; LAS bf16_t* STB = (LAS bf16_t*)(uintptr_t)aSTB;
;     static_assert(2 * 64 * LK * 2 + DVS * LK * 2 + 64 * LV * 2 + 64 * LS * 2 + DK * 4 + 2048 <= 159744, "GLA LDS map");
;     const int wid = tid >> 6, lane = tid & 63, l16 = lane & 15, quad = lane >> 4;
;     const int tr = wid >> 1, tv = wid / WPV, kt0 = (wid % WPV) * TPW;
;     const int vtr = (int)aVI + (8 * quad + (l16 >> 2)) * (LV * 2) + 8 * (lane & 3);
;     const int ktr = (int)aKD + (8 * quad + (l16 >> 2)) * (LK * 2) + 8 * (lane & 3);
;     ...
;     f32x4 st[TPW];
; #pragma unroll
;     for (int t = 0; t < TPW; ++t) st[t] = (f32x4){0.f, 0.f, 0.f, 0.f};
;     ...
;     typedef short vvec_t __attribute__((ext_vector_type(VPT)));
;     constexpr int NQV = RET ? 4 : 1, NLC = RET ? 1 : PPT;
;     bf16x8 qv[NQV], kv[NQV]; float lc[NLC]; bf16_t qr[NLC]; vvec_t vraw;
;     const int kx = tid % DK, pg = tid / DK;
;     const GAS bf16_t* Qg = (const GAS bf16_t*)Q; const GAS bf16_t* Kg = (const GAS bf16_t*)Kp; const GAS float* LFg = (const GAS float*)LF; const GAS bf16_t* Vg = (const GAS bf16_t*)V;
;     ...
;     GLA_LOAD(0);
;     for (int step = 0; step < 68; ++step) {
;         const int cidx = dir ? (step < 4 ? 3 - step : 71 - step) : step;
;         const long R0 = (long)b * TB + cidx * 64;
;         GLA_BAR();
;         {
; #pragma unroll
;             for (int t = 0; t < TPW; ++t)
; #pragma unroll
;                 for (int j = 0; j < 4; ++j) STB[(tv * 16 + quad * 4 + j) * LK + (kt0 + t) * 16 + l16] = f2bf(st[t][j]);
;             { const int p = tid >> 3, vg = tid & 7; const long row = R0 + (dir ? 63 - p : p); vraw = *(const GAS vvec_t*)(Vg + row * ldv + vcol0 + vg * VPT); }
;             float bl;
;             if constexpr (RET) {
.LBB0_69:
	s_bfe_u32 s28, s3, 0x10003
	s_bfe_u32 s24, s3, 0x20004
	s_lshl_b32 s22, s24, 2
	s_lshl_b32 s23, s28, 4
	s_or_b32 s22, s23, s22
	v_mov_b32_e32 v0, s22
	v_readlane_b32 s22, v254, 25
	v_readlane_b32 s23, v254, 26
	s_load_dwordx2 s[22:23], s[22:23], 0x80
	v_readlane_b32 s46, v254, 9
	v_readlane_b32 s29, v254, 4
	s_mov_b32 s30, s37
	v_readlane_b32 s41, v254, 6
	s_waitcnt lgkmcnt(0)
	global_load_dword v1, v0, s[22:23]
	s_ashr_i32 s22, s3, 6
	v_readlane_b32 s23, v254, 7
	v_readlane_b32 s45, v254, 8
	v_readlane_b32 s40, v254, 5
	s_mul_hi_i32 s43, s22, 0x1100
	s_mul_i32 s44, s22, 0x1100
	s_mov_b32 s22, 0x42fc0000
	s_bfe_i32 s25, s3, 0x10003
	v_add_u32_e32 v37, s29, v116
	v_add3_u32 v172, s29, v120, v78
	v_lshlrev_b32_e32 v36, 1, v69
	v_mov_b32_e32 v3, s43
	v_add_u32_e32 v38, s30, v36
	v_add_u32_e32 v40, s30, v170
	v_lshlrev_b64 v[86:87], 1, v[70:71]
	v_lshlrev_b64 v[88:89], 1, v[72:73]
	v_lshlrev_b64 v[90:91], 1, v[74:75]
	v_lshlrev_b64 v[92:93], 1, v[76:77]
	v_add_u32_e32 v41, s45, v170
	v_lshlrev_b32_e32 v49, 1, v70
	s_mov_b32 s31, s37
	v_add_u32_e32 v178, v40, v49
	v_add_u32_e32 v179, v41, v49
	v_lshlrev_b32_e32 v49, 1, v72
	v_lshlrev_b32_e32 v144, 1, v68
	v_add_u32_e32 v180, v40, v49
	v_add_u32_e32 v181, v41, v49
	v_lshlrev_b32_e32 v49, 1, v74
	v_add_u32_e32 v39, s46, v144
	v_add_u32_e32 v182, v40, v49
	v_add_u32_e32 v183, v41, v49
	v_lshlrev_b32_e32 v49, 1, v76
	v_mov_b32_e32 v0, 0
	v_add3_u32 v174, s45, v123, v36
	v_add_u32_e32 v175, s46, v36
	v_add3_u32 v176, s40, v125, v36
	v_lshl_add_u32 v36, v68, 2, s41
	v_add_u32_e32 v42, v39, v129
	v_add_u32_e32 v43, v39, v131
	v_add_u32_e32 v44, v39, v132
	v_add_u32_e32 v45, v39, v133
	v_add_u32_e32 v46, v39, v134
	v_add_u32_e32 v47, v39, v135
	v_add_u32_e32 v48, v39, v136
	v_add_u32_e32 v39, v39, v137
	v_add_u32_e32 v184, v40, v49
	v_lshlrev_b32_e32 v40, 1, v122
	v_mov_b32_e32 v83, v145
	v_mov_b32_e32 v85, v145
	s_mov_b32 s42, 0
	v_mov_b32_e32 v95, s43
	v_lshl_add_u32 v171, v118, 2, s41
	v_add_u32_e32 v177, v37, v128
	v_add_u32_e32 v185, v41, v49
	v_add3_u32 v199, s40, v138, v40
	v_add3_u32 v200, s40, v140, v40
	v_add3_u32 v201, s40, v142, v40
	v_add3_u32 v202, s40, v147, v40
	v_add_u32_e32 v203, v37, v151
	v_add_u32_e32 v210, v42, v130
	v_add_u32_e32 v211, v43, v130
	v_add_u32_e32 v212, v44, v130
	v_add_u32_e32 v213, v45, v130
	v_add_u32_e32 v214, v46, v130
	v_add_u32_e32 v215, v47, v130
	v_add_u32_e32 v216, v48, v130
	v_add_u32_e32 v217, v39, v130
	v_add_u32_e32 v218, v38, v121
	v_add_u32_e32 v219, v175, v155
	v_add_u32_e32 v220, v36, v162
	v_add_u32_e32 v221, v36, v163
	v_add_u32_e32 v222, v36, v164
	v_add_u32_e32 v223, v36, v165
	v_add_u32_e32 v224, v36, v166
	v_add_u32_e32 v225, v36, v167
	v_add_u32_e32 v226, v36, v168
	v_add_u32_e32 v227, v36, v169
	v_mov_b32_e32 v36, v0
	s_waitcnt vmcnt(0)
	v_cmp_lt_f32_e64 s[22:23], s22, v1
	v_mov_b32_e32 v38, v0
	v_mov_b32_e32 v39, v0
	v_cndmask_b32_e64 v2, 0, v195, s[22:23]
	v_sub_f32_e32 v1, v2, v1
	v_exp_f32_e32 v1, v1
	s_and_b64 s[22:23], s[22:23], exec
	s_cselect_b32 s22, 0xffffffc0, 0
	v_xor_b32_e32 v2, 63, v148
	v_ldexp_f32 v1, v1, s22
	v_sub_f32_e32 v1, 1.0, v1
	v_cmp_gt_f32_e64 s[22:23], s53, v1
	v_mov_b32_e32 v44, v0
	v_mov_b32_e32 v45, v0
	v_cndmask_b32_e64 v6, 0, v196, s[22:23]
	s_and_b64 s[22:23], s[22:23], exec
	s_cselect_b32 s22, 32, 0
	s_cmp_eq_u32 s28, 0
	v_ldexp_f32 v1, v1, s22
	s_cselect_b64 s[22:23], -1, 0
	v_log_f32_e32 v1, v1
	s_and_b64 s[28:29], s[22:23], exec
	s_cselect_b32 s28, s47, 0x1ad69000
	s_add_u32 s47, s0, s28
	v_cndmask_b32_e64 v2, v2, v148, s[22:23]
	s_addc_u32 s48, s1, 0
	s_and_b32 s25, s25, 0xc0
	s_lshl_b32 s28, s3, 7
	v_or_b32_e32 v94, s44, v2
	v_mul_f32_e32 v4, 0x3f317217, v1
	v_or_b32_e32 v2, s25, v2
	s_and_b32 s25, s28, 0x380
	s_mov_b32 s28, 0x3f317217
	s_lshl_b32 s36, s24, 9
	s_lshl_b32 s24, s24, 10
	v_fma_f32 v7, v1, s28, -v4
	v_or_b32_e32 v2, s44, v2
	s_or_b32 s30, s24, s25
	v_fmac_f32_e32 v7, 0x3377d1cf, v1
	v_lshlrev_b64 v[2:3], 11, v[2:3]
	s_mov_b32 s24, 0x7f800000
	v_fmac_f32_e32 v7, 0x3f317217, v1
	v_lshl_add_u64 v[4:5], s[90:91], 0, v[2:3]
	v_lshl_add_u64 v[2:3], s[26:27], 0, v[2:3]
	v_cmp_lt_f32_e64 s[24:25], |v1|, s24
	v_lshl_add_u64 v[4:5], v[4:5], 0, s[36:37]
	v_lshl_add_u64 v[2:3], v[2:3], 0, s[36:37]
	v_cndmask_b32_e64 v1, v1, v7, s[24:25]
	v_sub_f32_e32 v1, v1, v6
	v_lshl_add_u64 v[6:7], v[4:5], 0, v[86:87]
	v_lshl_add_u64 v[8:9], v[2:3], 0, v[86:87]
	v_lshl_add_u64 v[12:13], v[4:5], 0, v[88:89]
	v_lshl_add_u64 v[16:17], v[2:3], 0, v[88:89]
	v_lshl_add_u64 v[20:21], v[4:5], 0, v[90:91]
	v_lshl_add_u64 v[24:25], v[2:3], 0, v[90:91]
	v_lshl_add_u64 v[28:29], v[4:5], 0, v[92:93]
	v_lshl_add_u64 v[2:3], v[2:3], 0, v[92:93]
	global_load_dwordx4 v[4:7], v[6:7], off
	s_nop 0
	global_load_dwordx4 v[8:11], v[8:9], off
	s_nop 0
	global_load_dwordx4 v[12:15], v[12:13], off
	s_nop 0
	global_load_dwordx4 v[16:19], v[16:17], off
	s_nop 0
	global_load_dwordx4 v[20:23], v[20:21], off
	s_nop 0
	global_load_dwordx4 v[24:27], v[24:25], off
	s_nop 0
	global_load_dwordx4 v[28:31], v[28:29], off
	s_nop 0
	global_load_dwordx4 v[32:35], v[2:3], off
	s_add_u32 s28, s90, s36
	s_addc_u32 s29, s91, 0
	v_mul_f32_e32 v2, 0x42800000, v1
	v_mul_f32_e32 v1, v1, v79
	s_add_u32 s24, s26, s36
	v_mul_f32_e32 v3, 0x3fb8aa3b, v1
	v_mul_f32_e32 v1, 0xbfb8aa3b, v1
	v_mul_f32_e32 v2, 0x3fb8aa3b, v2
	v_exp_f32_e32 v100, v3
	v_exp_f32_e32 v102, v1
	s_addc_u32 s25, s27, 0
	v_lshl_add_u64 v[98:99], v[80:81], 0, s[30:31]
	v_exp_f32_e32 v173, v2
	s_add_u32 s30, s47, s30
	s_addc_u32 s31, s48, 0
	v_cndmask_b32_e64 v96, v119, v117, s[22:23]
	v_lshl_add_u64 v[2:3], s[30:31], 0, v[144:145]
	v_add_u32_e32 v1, s45, v127
; #define LAS __attribute__((address_space(3)))
; __device__ __forceinline__ bf16_t f2bf(float x) { return (bf16_t)(cvt_pk_bf16(x, x) & 0xffffu); }
; #define GLA_BAR() do { asm volatile("s_waitcnt lgkmcnt(0)" ::: "memory"); __builtin_amdgcn_s_barrier(); asm volatile("" ::: "memory"); } while (0)
; template <int DK, int DVS, bool RET> ...
;     ...
;     f32x4 st[TPW];
; #pragma unroll
;     for (int t = 0; t < TPW; ++t) st[t] = (f32x4){0.f, 0.f, 0.f, 0.f};
;     ...
;             for (int kk = 0; kk < DK / 32; ++kk) {
;                 const bf16x8 af = *(const LAS bf16x8*)(QD + (tr * 16 + l16) * LK + kk * 32 + quad * 8);
;                 const bf16x8 b0 = *(const LAS bf16x8*)(KD + (tcs * 16 + l16) * LK + kk * 32 + quad * 8);
;                 const bf16x8 b1 = *(const LAS bf16x8*)(KD + ((tcs + 1) * 16 + l16) * LK + kk * 32 + quad * 8);
;                 a0 = __builtin_amdgcn_mfma_f32_16x16x32_bf16(af, b0, a0, 0, 0, 0);
;                 a1 = __builtin_amdgcn_mfma_f32_16x16x32_bf16(af, b1, a1, 0, 0, 0);
;                 asm volatile("" ::: "memory");
;             }
; #pragma unroll
;             for (int j = 0; j < 4; ++j) { const int p = tr * 16 + quad * 4 + j, s0 = tcs * 16 + l16, s1 = s0 + 16;
;                 AT[p * LS + s0] = f2bf((s0 <= p) ? a0[j] : 0.f); AT[p * LS + s1] = f2bf((s1 <= p) ? a1[j] : 0.f); }
;         }
;         GLA_BAR();
; #pragma unroll
;         for (int t = 0; t < NOT; ++t) { const int tc = (wid & 1) * NOT + t; f32x4 acc = {0.f, 0.f, 0.f, 0.f};
; #pragma unroll
;             for (int kk = 0; kk < DK / 32; ++kk) {
;                 const bf16x8 af = *(const LAS bf16x8*)(QD + (tr * 16 + l16) * LK + kk * 32 + quad * 8);
;                 const bf16x8 bf = *(const LAS bf16x8*)(STB + (tc * 16 + l16) * LK + kk * 32 + quad * 8);
;                 acc = __builtin_amdgcn_mfma_f32_16x16x32_bf16(af, bf, acc, 0, 0, 0);
;                 if ((kk & 3) == 3) asm volatile("" ::: "memory"); }
	v_cndmask_b32_e64 v104, v150, v124, s[22:23]
	v_cndmask_b32_e64 v108, v152, v139, s[22:23]
	v_cndmask_b32_e64 v110, v153, v141, s[22:23]
	v_cndmask_b32_e64 v112, v154, v143, s[22:23]
	v_ashrrev_i32_e32 v97, 31, v96
	v_add_u32_e32 v144, v37, v126
	v_ashrrev_i32_e32 v105, 31, v104
	v_lshl_add_u64 v[106:107], v[2:3], 0, v[82:83]
	v_ashrrev_i32_e32 v109, 31, v108
	v_ashrrev_i32_e32 v111, 31, v110
	v_ashrrev_i32_e32 v113, 31, v112
	v_lshl_add_u64 v[114:115], v[2:3], 0, v[84:85]
	v_add_u32_e32 v83, v1, v129
	v_add_u32_e32 v85, v1, v131
	v_add_u32_e32 v204, v1, v156
	v_add_u32_e32 v205, v1, v157
	v_add_u32_e32 v206, v1, v158
	v_add_u32_e32 v207, v1, v159
	v_add_u32_e32 v208, v1, v160
	v_add_u32_e32 v209, v1, v161
	v_mov_b32_e32 v103, v102
	v_mov_b32_e32 v101, v100
	s_mov_b32 s45, 0
	v_mov_b32_e32 v1, v0
	v_mov_b32_e32 v2, v0
	v_mov_b32_e32 v3, v0
	v_mov_b32_e32 v37, v0
	v_mov_b32_e32 v46, v0
	v_mov_b32_e32 v47, v0
	v_mov_b32_e32 v40, v0
	v_mov_b32_e32 v41, v0
	v_mov_b32_e32 v42, v0
	v_mov_b32_e32 v43, v0
	v_mov_b32_e32 v52, v0
	v_mov_b32_e32 v53, v0
	v_mov_b32_e32 v54, v0
	v_mov_b32_e32 v55, v0
	v_mov_b32_e32 v48, v0
	v_mov_b32_e32 v49, v0
	v_mov_b32_e32 v50, v0
	v_mov_b32_e32 v51, v0
	v_mov_b32_e32 v60, v0
	v_mov_b32_e32 v61, v0
	v_mov_b32_e32 v62, v0
	v_mov_b32_e32 v63, v0
	v_mov_b32_e32 v56, v0
	v_mov_b32_e32 v57, v0
	v_mov_b32_e32 v58, v0
	v_mov_b32_e32 v59, v0
	v_subrev_u32_e32 v95, s44, v94
	v_lshl_add_u32 v86, v95, 11, v86
	v_lshl_add_u32 v88, v95, 11, v88
	v_lshl_add_u32 v90, v95, 11, v90
	v_lshl_add_u32 v92, v95, 11, v92
	v_and_b32_e32 v64, 15, v148
	v_bfe_u32 v65, v148, 4, 2
	v_lshlrev_b32_e32 v65, 2, v65
	v_sub_u32_e32 v64, v64, v65
	v_mul_i32_i24_e32 v64, 0x20e, v64
	v_add_u32_e32 v210, v210, v64
	s_branch .LBB0_71
.LBB0_70:
	s_waitcnt lgkmcnt(0)
	s_barrier
	v_add_u32_e32 v198, v175, v123
	ds_read_b128 v[232:235], v218
	ds_read_b128 v[236:239], v174
	ds_read_b128 v[240:243], v174 offset:8448
	ds_read_b128 v[244:247], v198
	ds_read_b128 v[248:251], v219
	s_waitcnt lgkmcnt(3)
	v_mfma_f32_16x16x32_bf16 v[228:231], v[232:235], v[236:239], 0
	ds_read_b128 v[212:215], v218 offset:64
	ds_read_b128 v[236:239], v174 offset:64
	s_waitcnt lgkmcnt(4)
	v_mfma_f32_16x16x32_bf16 v[64:67], v[232:235], v[240:243], 0
	ds_read_b128 v[240:243], v174 offset:8512
	s_waitcnt lgkmcnt(4)
	v_mfma_f32_16x16x32_bf16 v[220:223], v[232:235], v[244:247], 0
	ds_read_b128 v[244:247], v198 offset:64
	s_waitcnt lgkmcnt(4)
	v_mfma_f32_16x16x32_bf16 v[224:227], v[232:235], v[248:251], 0
	ds_read_b128 v[248:251], v219 offset:64
	s_waitcnt lgkmcnt(3)
	v_mfma_f32_16x16x32_bf16 v[228:231], v[212:215], v[236:239], v[228:231]
	ds_read_b128 v[232:235], v218 offset:128
	ds_read_b128 v[236:239], v174 offset:128
	s_waitcnt lgkmcnt(4)
	v_mfma_f32_16x16x32_bf16 v[64:67], v[212:215], v[240:243], v[64:67]
	ds_read_b128 v[240:243], v174 offset:8576
	s_waitcnt lgkmcnt(4)
	v_mfma_f32_16x16x32_bf16 v[220:223], v[212:215], v[244:247], v[220:223]
	ds_read_b128 v[244:247], v198 offset:128
	s_waitcnt lgkmcnt(4)
	v_mfma_f32_16x16x32_bf16 v[224:227], v[212:215], v[248:251], v[224:227]
	ds_read_b128 v[248:251], v219 offset:128
	s_waitcnt lgkmcnt(3)
	v_mfma_f32_16x16x32_bf16 v[228:231], v[232:235], v[236:239], v[228:231]
	ds_read_b128 v[212:215], v218 offset:192
	ds_read_b128 v[236:239], v174 offset:192
	s_waitcnt lgkmcnt(4)
	v_mfma_f32_16x16x32_bf16 v[64:67], v[232:235], v[240:243], v[64:67]
	ds_read_b128 v[240:243], v174 offset:8640
	s_waitcnt lgkmcnt(4)
	v_mfma_f32_16x16x32_bf16 v[220:223], v[232:235], v[244:247], v[220:223]
	ds_read_b128 v[244:247], v198 offset:192
	s_waitcnt lgkmcnt(4)
	v_mfma_f32_16x16x32_bf16 v[224:227], v[232:235], v[248:251], v[224:227]
	ds_read_b128 v[248:251], v219 offset:192
	s_waitcnt lgkmcnt(3)
	v_mfma_f32_16x16x32_bf16 v[228:231], v[212:215], v[236:239], v[228:231]
	ds_read_b128 v[232:235], v218 offset:256
	ds_read_b128 v[236:239], v174 offset:256
	s_waitcnt lgkmcnt(4)
	v_mfma_f32_16x16x32_bf16 v[64:67], v[212:215], v[240:243], v[64:67]
	ds_read_b128 v[240:243], v174 offset:8704
	s_waitcnt lgkmcnt(4)
	v_mfma_f32_16x16x32_bf16 v[220:223], v[212:215], v[244:247], v[220:223]
	ds_read_b128 v[244:247], v198 offset:256
	s_waitcnt lgkmcnt(4)
	v_mfma_f32_16x16x32_bf16 v[224:227], v[212:215], v[248:251], v[224:227]
	ds_read_b128 v[248:251], v219 offset:256
	s_waitcnt lgkmcnt(3)
	v_mfma_f32_16x16x32_bf16 v[228:231], v[232:235], v[236:239], v[228:231]
	ds_read_b128 v[212:215], v218 offset:320
	ds_read_b128 v[236:239], v174 offset:320
	s_waitcnt lgkmcnt(4)
	v_mfma_f32_16x16x32_bf16 v[64:67], v[232:235], v[240:243], v[64:67]
	ds_read_b128 v[240:243], v174 offset:8768
	s_waitcnt lgkmcnt(4)
	v_mfma_f32_16x16x32_bf16 v[220:223], v[232:235], v[244:247], v[220:223]
	ds_read_b128 v[244:247], v198 offset:320
	s_waitcnt lgkmcnt(4)
	v_mfma_f32_16x16x32_bf16 v[224:227], v[232:235], v[248:251], v[224:227]
	ds_read_b128 v[248:251], v219 offset:320
	s_waitcnt lgkmcnt(3)
	v_mfma_f32_16x16x32_bf16 v[228:231], v[212:215], v[236:239], v[228:231]
	ds_read_b128 v[232:235], v218 offset:384
	ds_read_b128 v[236:239], v174 offset:384
	s_waitcnt lgkmcnt(4)
	v_mfma_f32_16x16x32_bf16 v[64:67], v[212:215], v[240:243], v[64:67]
	ds_read_b128 v[240:243], v174 offset:8832
	s_waitcnt lgkmcnt(4)
	v_mfma_f32_16x16x32_bf16 v[220:223], v[212:215], v[244:247], v[220:223]
	ds_read_b128 v[244:247], v198 offset:384
	s_waitcnt lgkmcnt(4)
	v_mfma_f32_16x16x32_bf16 v[224:227], v[212:215], v[248:251], v[224:227]
	ds_read_b128 v[248:251], v219 offset:384
	s_waitcnt lgkmcnt(3)
	v_mfma_f32_16x16x32_bf16 v[228:231], v[232:235], v[236:239], v[228:231]
	ds_read_b128 v[212:215], v218 offset:448
	ds_read_b128 v[236:239], v174 offset:448
	s_waitcnt lgkmcnt(4)
; #define LAS __attribute__((address_space(3)))
; template <int DK, int DVS, bool RET> ...
;     ...
;             for (int j = 0; j < 4; ++j) { const int p = tr * 16 + quad * 4 + j, s0 = tcs * 16 + l16, s1 = s0 + 16;
;                 AT[p * LS + s0] = f2bf((s0 <= p) ? a0[j] : 0.f); AT[p * LS + s1] = f2bf((s1 <= p) ? a1[j] : 0.f); }
;         }
;         GLA_BAR();
; #pragma unroll
;         for (int t = 0; t < NOT; ++t) { const int tc = (wid & 1) * NOT + t; f32x4 acc = {0.f, 0.f, 0.f, 0.f};
; #pragma unroll
;             for (int kk = 0; kk < DK / 32; ++kk) {
;                 const bf16x8 af = *(const LAS bf16x8*)(QD + (tr * 16 + l16) * LK + kk * 32 + quad * 8);
;                 const bf16x8 bf = *(const LAS bf16x8*)(STB + (tc * 16 + l16) * LK + kk * 32 + quad * 8);
;                 acc = __builtin_amdgcn_mfma_f32_16x16x32_bf16(af, bf, acc, 0, 0, 0);
;                 if ((kk & 3) == 3) asm volatile("" ::: "memory"); }
;             { s16x4 v00, v01, v10, v11; const int vb = vtr + tc * 32;
;                 TRR(v00, vb, 0); TRR(v01, vb, 4 * LV * 2); TRR(v10, vb, 32 * LV * 2); TRR(v11, vb, 36 * LV * 2);
;                 const bf16x8 a0 = *(const LAS bf16x8*)(AT + (tr * 16 + l16) * LS + quad * 8), a1 = *(const LAS bf16x8*)(AT + (tr * 16 + l16) * LS + 32 + quad * 8);
;                 asm volatile("s_waitcnt lgkmcnt(0)" ::: "memory"); __builtin_amdgcn_sched_barrier(0);
;                 acc = __builtin_amdgcn_mfma_f32_16x16x32_bf16(a0, TRFRAG(v00, v01), acc, 0, 0, 0);
;                 acc = __builtin_amdgcn_mfma_f32_16x16x32_bf16(a1, TRFRAG(v10, v11), acc, 0, 0, 0); }
; #pragma unroll
;             for (int j = 0; j < 4; ++j) { const int p = tr * 16 + quad * 4 + j; const long row = R0 + (dir ? 63 - p : p);
;                 ((GAS bf16_t*)Od)[row * ldv + vcol0 + tc * 16 + l16] = f2bf(acc[j]); }
;         }
;         { s16x4 a00, a01, a10, a11; const int vb = vtr + tv * 32;
;             TRR(a00, vb, 0); TRR(a01, vb, 4 * LV * 2); TRR(a10, vb, 32 * LV * 2); TRR(a11, vb, 36 * LV * 2);
; #pragma unroll
;             for (int t0 = 0; t0 < TPW; t0 += 2) {
;                 s16x4 b[2][4];
; #pragma unroll
;                 for (int u = 0; u < 2; ++u) { const int kb = ktr + (kt0 + t0 + u) * 32;
;                     TRR(b[u][0], kb, 0); TRR(b[u][1], kb, 4 * LK * 2); TRR(b[u][2], kb, 32 * LK * 2); TRR(b[u][3], kb, 36 * LK * 2); }
	v_mfma_f32_16x16x32_bf16 v[64:67], v[232:235], v[240:243], v[64:67]
	ds_read_b128 v[240:243], v174 offset:8896
	s_waitcnt lgkmcnt(4)
	v_mfma_f32_16x16x32_bf16 v[220:223], v[232:235], v[244:247], v[220:223]
	ds_read_b128 v[244:247], v198 offset:448
	s_waitcnt lgkmcnt(4)
	v_mfma_f32_16x16x32_bf16 v[224:227], v[232:235], v[248:251], v[224:227]
	ds_read_b128 v[248:251], v219 offset:448
	s_waitcnt lgkmcnt(3)
	v_mfma_f32_16x16x32_bf16 v[228:231], v[212:215], v[236:239], v[228:231]
	s_waitcnt lgkmcnt(2)
	v_mfma_f32_16x16x32_bf16 v[64:67], v[212:215], v[240:243], v[64:67]
	s_waitcnt lgkmcnt(1)
	v_mfma_f32_16x16x32_bf16 v[220:223], v[212:215], v[244:247], v[220:223]
	s_waitcnt lgkmcnt(0)
	v_mfma_f32_16x16x32_bf16 v[224:227], v[212:215], v[248:251], v[224:227]
	s_nop 6
	v_cvt_pk_bf16_f32 v64, v64, s0
	v_cndmask_b32_e64 v64, v64, 0, s[8:9]
	ds_write_b16 v199, v64 offset:32
	v_cvt_pk_bf16_f32 v64, v229, s0
	v_cndmask_b32_e64 v64, v64, 0, s[10:11]
	ds_write_b16 v200, v64
	v_cvt_pk_bf16_f32 v64, v65, s0
	v_cndmask_b32_e64 v64, v64, 0, s[12:13]
	ds_write_b16 v200, v64 offset:32
	v_cvt_pk_bf16_f32 v64, v230, s0
	v_cndmask_b32_e64 v64, v64, 0, s[14:15]
	ds_write_b16 v201, v64
	v_cvt_pk_bf16_f32 v64, v66, s0
	v_cndmask_b32_e64 v64, v64, 0, s[16:17]
	ds_write_b16 v201, v64 offset:32
	v_cvt_pk_bf16_f32 v64, v231, s0
	v_cndmask_b32_e64 v64, v64, 0, s[18:19]
	v_cvt_pk_bf16_f32 v198, v228, s0
	ds_write_b16 v202, v64
	v_cvt_pk_bf16_f32 v64, v67, s0
	v_cndmask_b32_e64 v198, v198, 0, s[6:7]
	v_cndmask_b32_e64 v64, v64, 0, s[20:21]
	ds_write_b16 v199, v198
	ds_write_b16 v202, v64 offset:32
	s_waitcnt lgkmcnt(0)
	s_barrier
	ds_read_b128 v[248:251], v176
	ds_read_b128 v[212:215], v176 offset:64
	ds_read_b64_tr_b16 v[232:233], v203 offset:0
	ds_read_b64_tr_b16 v[234:235], v203 offset:0x240
	ds_read_b64_tr_b16 v[236:237], v203 offset:0x1200
	ds_read_b64_tr_b16 v[238:239], v203 offset:0x1440
	ds_read_b64_tr_b16 v[240:241], v177 offset:0
	ds_read_b64_tr_b16 v[242:243], v177 offset:0x240
	ds_read_b64_tr_b16 v[244:245], v177 offset:0x1200
	ds_read_b64_tr_b16 v[246:247], v177 offset:0x1440
	s_waitcnt lgkmcnt(6)
	v_mfma_f32_16x16x32_bf16 v[220:223], v[248:251], v[232:235], v[220:223]
	s_waitcnt lgkmcnt(4)
	v_mfma_f32_16x16x32_bf16 v[220:223], v[212:215], v[236:239], v[220:223]
	s_waitcnt lgkmcnt(2)
	v_mfma_f32_16x16x32_bf16 v[224:227], v[248:251], v[240:243], v[224:227]
	s_waitcnt lgkmcnt(0)
	v_mfma_f32_16x16x32_bf16 v[224:227], v[212:215], v[244:247], v[224:227]
	v_lshl_add_u64 v[232:233], s[30:31], 0, v[104:105]
	v_lshlrev_b64 v[232:233], 12, v[232:233]
	v_lshl_add_u64 v[234:235], s[30:31], 0, v[108:109]
	v_lshlrev_b64 v[234:235], 12, v[234:235]
	v_lshl_add_u64 v[236:237], s[30:31], 0, v[110:111]
	v_lshlrev_b64 v[236:237], 12, v[236:237]
	v_lshl_add_u64 v[238:239], s[30:31], 0, v[112:113]
	v_lshlrev_b64 v[238:239], 12, v[238:239]
	s_nop 1
	v_cvt_pk_bf16_f32 v198, v220, s0
	v_lshl_add_u64 v[240:241], v[106:107], 0, v[232:233]
	global_store_short v[240:241], v198, off
	v_cvt_pk_bf16_f32 v242, v221, s0
	v_lshl_add_u64 v[244:245], v[106:107], 0, v[234:235]
	global_store_short v[244:245], v242, off
	v_cvt_pk_bf16_f32 v198, v222, s0
	v_lshl_add_u64 v[240:241], v[106:107], 0, v[236:237]
	global_store_short v[240:241], v198, off
	v_cvt_pk_bf16_f32 v242, v223, s0
	v_lshl_add_u64 v[244:245], v[106:107], 0, v[238:239]
	global_store_short v[244:245], v242, off
	s_nop 3
	v_cvt_pk_bf16_f32 v198, v224, s0
	v_lshl_add_u64 v[240:241], v[114:115], 0, v[232:233]
	global_store_short v[240:241], v198, off
	v_cvt_pk_bf16_f32 v242, v225, s0
	v_lshl_add_u64 v[244:245], v[114:115], 0, v[234:235]
	global_store_short v[244:245], v242, off
	v_cvt_pk_bf16_f32 v198, v226, s0
	v_lshl_add_u64 v[240:241], v[114:115], 0, v[236:237]
	global_store_short v[240:241], v198, off
	v_cvt_pk_bf16_f32 v242, v227, s0
	v_lshl_add_u64 v[244:245], v[114:115], 0, v[238:239]
	global_store_short v[244:245], v242, off
	ds_read_b64_tr_b16 v[64:65], v144 offset:0
	ds_read_b64_tr_b16 v[66:67], v144 offset:0x240
	ds_read_b64_tr_b16 v[228:229], v144 offset:0x1200
	ds_read_b64_tr_b16 v[230:231], v144 offset:0x1440
	ds_read_b64_tr_b16 v[232:233], v83 offset:0
	ds_read_b64_tr_b16 v[234:235], v83 offset:0x840
	ds_read_b64_tr_b16 v[236:237], v83 offset:0x4200
	ds_read_b64_tr_b16 v[238:239], v83 offset:0x4a40
	ds_read_b64_tr_b16 v[240:241], v85 offset:0
	ds_read_b64_tr_b16 v[242:243], v85 offset:0x840
	ds_read_b64_tr_b16 v[244:245], v85 offset:0x4200
	ds_read_b64_tr_b16 v[246:247], v85 offset:0x4a40
	s_waitcnt lgkmcnt(0)
	s_nop 0
	v_mfma_f32_16x16x32_bf16 v[56:59], v[232:235], v[64:67], v[56:59]
	ds_read_b64_tr_b16 v[232:233], v204 offset:0
	ds_read_b64_tr_b16 v[234:235], v204 offset:0x840
	v_mfma_f32_16x16x32_bf16 v[56:59], v[236:239], v[228:231], v[56:59]
	ds_read_b64_tr_b16 v[236:237], v204 offset:0x4200
	ds_read_b64_tr_b16 v[238:239], v204 offset:0x4a40
	v_mfma_f32_16x16x32_bf16 v[60:63], v[240:243], v[64:67], v[60:63]
	ds_read_b64_tr_b16 v[240:241], v205 offset:0
	ds_read_b64_tr_b16 v[242:243], v205 offset:0x840
	v_mfma_f32_16x16x32_bf16 v[60:63], v[244:247], v[228:231], v[60:63]
	ds_read_b64_tr_b16 v[244:245], v205 offset:0x4200
	ds_read_b64_tr_b16 v[246:247], v205 offset:0x4a40
	s_waitcnt lgkmcnt(0)
	v_mfma_f32_16x16x32_bf16 v[48:51], v[232:235], v[64:67], v[48:51]
	ds_read_b64_tr_b16 v[232:233], v206 offset:0
	ds_read_b64_tr_b16 v[234:235], v206 offset:0x840
	v_mfma_f32_16x16x32_bf16 v[48:51], v[236:239], v[228:231], v[48:51]
	ds_read_b64_tr_b16 v[236:237], v206 offset:0x4200
	ds_read_b64_tr_b16 v[238:239], v206 offset:0x4a40
	v_mfma_f32_16x16x32_bf16 v[52:55], v[240:243], v[64:67], v[52:55]
	ds_read_b64_tr_b16 v[240:241], v207 offset:0
	ds_read_b64_tr_b16 v[242:243], v207 offset:0x840
	v_mfma_f32_16x16x32_bf16 v[52:55], v[244:247], v[228:231], v[52:55]
	ds_read_b64_tr_b16 v[244:245], v207 offset:0x4200
	ds_read_b64_tr_b16 v[246:247], v207 offset:0x4a40
	s_waitcnt lgkmcnt(0)
; #define GAS __attribute__((address_space(1)))
; __device__ __forceinline__ bf16_t f2bf(float x) { return (bf16_t)(cvt_pk_bf16(x, x) & 0xffffu); }
; #define GLA_BAR() do { asm volatile("s_waitcnt lgkmcnt(0)" ::: "memory"); __builtin_amdgcn_s_barrier(); asm volatile("" ::: "memory"); } while (0)
; template <int DK, int DVS, bool RET> ...
;     ...
;     for (int step = 0; step < 68; ++step) {
;         const int cidx = dir ? (step < 4 ? 3 - step : 71 - step) : step;
;         const long R0 = (long)b * TB + cidx * 64;
;         GLA_BAR();
;         {
; #pragma unroll
;             for (int t = 0; t < TPW; ++t)
; #pragma unroll
;                 for (int j = 0; j < 4; ++j) STB[(tv * 16 + quad * 4 + j) * LK + (kt0 + t) * 16 + l16] = f2bf(st[t][j]);
;             { const int p = tid >> 3, vg = tid & 7; const long row = R0 + (dir ? 63 - p : p); vraw = *(const GAS vvec_t*)(Vg + row * ldv + vcol0 + vg * VPT); }
;     ...
;                 for (int u = 0; u < 2; ++u) { const int t = t0 + u;
;                     st[t] = __builtin_amdgcn_mfma_f32_16x16x32_bf16(TRFRAG(a00, a01), TRFRAG(b[u][0], b[u][1]), st[t], 0, 0, 0);
;                     st[t] = __builtin_amdgcn_mfma_f32_16x16x32_bf16(TRFRAG(a10, a11), TRFRAG(b[u][2], b[u][3]), st[t], 0, 0, 0); }
;             }
; #pragma unroll
;             for (int t = 0; t < TPW; ++t) st[t] = st[t] * EL[(kt0 + t) * 16 + l16];
	v_mfma_f32_16x16x32_bf16 v[40:43], v[232:235], v[64:67], v[40:43]
	ds_read_b64_tr_b16 v[232:233], v208 offset:0
	ds_read_b64_tr_b16 v[234:235], v208 offset:0x840
	v_mfma_f32_16x16x32_bf16 v[40:43], v[236:239], v[228:231], v[40:43]
	ds_read_b64_tr_b16 v[236:237], v208 offset:0x4200
	ds_read_b64_tr_b16 v[238:239], v208 offset:0x4a40
	v_mfma_f32_16x16x32_bf16 v[44:47], v[240:243], v[64:67], v[44:47]
	ds_read_b64_tr_b16 v[240:241], v209 offset:0
	ds_read_b64_tr_b16 v[242:243], v209 offset:0x840
	v_mfma_f32_16x16x32_bf16 v[44:47], v[244:247], v[228:231], v[44:47]
	ds_read_b64_tr_b16 v[244:245], v209 offset:0x4200
	ds_read_b64_tr_b16 v[246:247], v209 offset:0x4a40
	s_waitcnt lgkmcnt(0)
	v_mfma_f32_16x16x32_bf16 v[36:39], v[232:235], v[64:67], v[36:39]
	s_add_i32 s42, s42, -1
	s_cmpk_lg_i32 s42, 0xffbc
	s_mov_b32 s45, s36
	v_mfma_f32_16x16x32_bf16 v[0:3], v[240:243], v[64:67], v[0:3]
	v_mov_b32_e32 v64, v173
	v_mfma_f32_16x16x32_bf16 v[36:39], v[236:239], v[228:231], v[36:39]
	v_mfma_f32_16x16x32_bf16 v[0:3], v[244:247], v[228:231], v[0:3]
	v_pk_mul_f32 v[58:59], v[58:59], v[64:65] op_sel_hi:[1,0]
	v_pk_mul_f32 v[56:57], v[56:57], v[64:65] op_sel_hi:[1,0]
	v_pk_mul_f32 v[62:63], v[62:63], v[64:65] op_sel_hi:[1,0]
	v_pk_mul_f32 v[60:61], v[60:61], v[64:65] op_sel_hi:[1,0]
	v_pk_mul_f32 v[50:51], v[50:51], v[64:65] op_sel_hi:[1,0]
	v_pk_mul_f32 v[48:49], v[48:49], v[64:65] op_sel_hi:[1,0]
	v_pk_mul_f32 v[54:55], v[54:55], v[64:65] op_sel_hi:[1,0]
	v_pk_mul_f32 v[52:53], v[52:53], v[64:65] op_sel_hi:[1,0]
	v_pk_mul_f32 v[42:43], v[42:43], v[64:65] op_sel_hi:[1,0]
	v_pk_mul_f32 v[40:41], v[40:41], v[64:65] op_sel_hi:[1,0]
	v_pk_mul_f32 v[46:47], v[46:47], v[64:65] op_sel_hi:[1,0]
	v_pk_mul_f32 v[44:45], v[44:45], v[64:65] op_sel_hi:[1,0]
	v_pk_mul_f32 v[38:39], v[38:39], v[64:65] op_sel_hi:[1,0]
	v_pk_mul_f32 v[36:37], v[36:37], v[64:65] op_sel_hi:[1,0]
	v_pk_mul_f32 v[2:3], v[2:3], v[64:65] op_sel_hi:[1,0]
	v_pk_mul_f32 v[0:1], v[0:1], v[64:65] op_sel_hi:[1,0]
	s_cbranch_scc0 .LBB0_68
.LBB0_71:
	s_cmp_gt_u32 s45, 3
	s_cselect_b32 s30, 0x47, 3
	s_add_i32 s36, s30, s42
	s_and_b64 s[30:31], s[22:23], exec
	s_cselect_b32 s30, s45, s36
	s_lshl_b32 s30, s30, 6
	s_ashr_i32 s31, s30, 31
	s_add_u32 s30, s44, s30
	s_addc_u32 s31, s43, s31
	v_lshl_add_u64 v[214:215], s[30:31], 0, v[96:97]
	v_lshlrev_b64 v[214:215], 12, v[214:215]
	v_lshl_add_u64 v[214:215], v[98:99], 0, v[214:215]
	global_load_dwordx4 v[212:215], v[214:215], off
	s_add_i32 s39, s45, 1
	s_min_i32 s39, s39, 0x43
	s_cmp_gt_u32 s39, 3
	s_cselect_b32 s38, 0x47, 3
	s_sub_i32 s38, s38, s39
	s_and_b64 s[54:55], s[22:23], exec
	s_cselect_b32 s38, s39, s38
	s_lshl_b32 s38, s38, 6
	s_add_u32 s38, s44, s38
	s_addc_u32 s39, s43, 0
	s_lshl_b64 s[38:39], s[38:39], 11
	s_add_u32 s54, s24, s38
	s_addc_u32 s55, s25, s39
	s_add_u32 s38, s28, s38
	s_addc_u32 s39, s29, s39
	s_waitcnt lgkmcnt(0)
	s_barrier
; #define LAS __attribute__((address_space(3)))
; #define GAS __attribute__((address_space(1)))
; __device__ __forceinline__ bf16_t f2bf(float x) { return (bf16_t)(cvt_pk_bf16(x, x) & 0xffffu); }
; __device__ __forceinline__ float bf2f(bf16_t v) { return __uint_as_float((unsigned)v << 16); }
; template <int DK, int DVS, bool RET> ...
;     ...
;             for (int t = 0; t < TPW; ++t)
; #pragma unroll
;                 for (int j = 0; j < 4; ++j) STB[(tv * 16 + quad * 4 + j) * LK + (kt0 + t) * 16 + l16] = f2bf(st[t][j]);
;             { const int p = tid >> 3, vg = tid & 7; const long row = R0 + (dir ? 63 - p : p); vraw = *(const GAS vvec_t*)(Vg + row * ldv + vcol0 + vg * VPT); }
;             float bl;
;             if constexpr (RET) {
;                 static_assert(!RET || DK == 256, "retention prep: 64 x 256 = 2048 eight-wide items, four per thread");
;                 bl = 64.f * lg;
; #pragma unroll
;                 for (int j = 0; j < 4; ++j) { const int it = tid + 512 * j, p = it & 63, k0 = (it >> 6) * 8; const float bb = (float)(p + 1) * lg;
;                     const float eq = __expf(bb), ek = __expf(-bb); float a[8], c[8];
; #pragma unroll
;                     for (int e = 0; e < 8; ++e) { a[e] = bf2f((bf16_t)qv[j][e]) * eq; c[e] = bf2f((bf16_t)kv[j][e]) * ek; }
;                     *(LAS u32x4*)(QD + p * LK + k0) = pack8(a); *(LAS u32x4*)(KD + p * LK + k0) = pack8(c); }
;             } else {
;                 float c = 0.f;
; #pragma unroll
;                 for (int i = 0; i < PPT; ++i) c += lc[i];
;                 TOT[pg * 128 + kx] = c;
;                 GLA_BAR();
;                 float off = 0.f; bl = 0.f;
; #pragma unroll
;                 for (int g = 0; g < NPG; ++g) { const float t = TOT[g * 128 + kx]; if (g < pg) off += t; bl += t; }
;                 float bb = off;
; #pragma unroll
;                 for (int i = 0; i < PPT; ++i) { const int p = pg * PPT + i;
;                     const float qf = bf2f(qr[i]), kf = 1.f - __expf(lc[i]); bb += lc[i];
;                     QD[p * LK + kx] = f2bf(qf * __expf(bb)); KD[p * LK + kx] = f2bf(kf * __expf(-bb)); }
;             }
;             if (pg == 0) EL[kx] = __expf(bl);
;             { const int p = tid >> 3, vg = tid & 7; *(LAS vvec_t*)(VI + p * LV + vg * VPT) = vraw; }
;         }
;         if (step + 1 < 68) GLA_LOAD(step + 1);
	v_cvt_pk_bf16_f32 v64, v56, v57
	v_cvt_pk_bf16_f32 v65, v58, v59
	ds_write_b64 v210, v[64:65]
	s_cmp_gt_u32 s45, 3
	s_cselect_b32 s30, 0x47, 3
	v_cvt_pk_bf16_f32 v66, v60, v61
	v_cvt_pk_bf16_f32 v67, v62, v63
	ds_write_b64 v210, v[66:67] offset:32
	s_add_i32 s36, s30, s42
	s_and_b64 s[30:31], s[22:23], exec
	v_cvt_pk_bf16_f32 v64, v48, v49
	v_cvt_pk_bf16_f32 v65, v50, v51
	ds_write_b64 v210, v[64:65] offset:64
	s_cselect_b32 s30, s45, s36
	s_lshl_b32 s30, s30, 6
	v_cvt_pk_bf16_f32 v66, v52, v53
	v_cvt_pk_bf16_f32 v67, v54, v55
	ds_write_b64 v210, v[66:67] offset:96
	s_ashr_i32 s31, s30, 31
	s_add_u32 s30, s44, s30
	v_cvt_pk_bf16_f32 v64, v40, v41
	v_cvt_pk_bf16_f32 v65, v42, v43
	ds_write_b64 v210, v[64:65] offset:128
	s_addc_u32 s31, s43, s31
	v_cvt_pk_bf16_f32 v66, v44, v45
	v_cvt_pk_bf16_f32 v67, v46, v47
	ds_write_b64 v210, v[66:67] offset:160
	v_cvt_pk_bf16_f32 v64, v36, v37
	v_cvt_pk_bf16_f32 v65, v38, v39
	ds_write_b64 v210, v[64:65] offset:192
	v_cvt_pk_bf16_f32 v66, v0, v1
	v_cvt_pk_bf16_f32 v67, v2, v3
	ds_write_b64 v210, v[66:67] offset:224
	s_waitcnt vmcnt(7)
	v_and_b32_e32 v231, 0xffff0000, v8
	v_lshlrev_b32_e32 v230, 16, v8
	v_and_b32_e32 v229, 0xffff0000, v4
	v_lshlrev_b32_e32 v228, 16, v4
	v_pk_mul_f32 v[232:233], v[102:103], v[230:231]
	v_and_b32_e32 v231, 0xffff0000, v5
	v_lshlrev_b32_e32 v230, 16, v5
	v_and_b32_e32 v237, 0xffff0000, v6
	v_lshlrev_b32_e32 v236, 16, v6
	v_and_b32_e32 v241, 0xffff0000, v7
	v_lshlrev_b32_e32 v240, 16, v7
	v_pk_mul_f32 v[228:229], v[100:101], v[228:229]
	v_pk_mul_f32 v[230:231], v[100:101], v[230:231]
	v_and_b32_e32 v235, 0xffff0000, v9
	v_lshlrev_b32_e32 v234, 16, v9
	v_pk_mul_f32 v[236:237], v[100:101], v[236:237]
	v_and_b32_e32 v239, 0xffff0000, v10
	v_lshlrev_b32_e32 v238, 16, v10
	v_pk_mul_f32 v[240:241], v[100:101], v[240:241]
	v_and_b32_e32 v243, 0xffff0000, v11
	v_lshlrev_b32_e32 v242, 16, v11
	global_load_dwordx4 v[4:7], v86, s[38:39]
	global_load_dwordx4 v[8:11], v86, s[54:55]
	v_pk_mul_f32 v[234:235], v[102:103], v[234:235]
	v_pk_mul_f32 v[238:239], v[102:103], v[238:239]
	v_pk_mul_f32 v[242:243], v[102:103], v[242:243]
	v_cvt_pk_bf16_f32 v228, v228, v229
	v_cvt_pk_bf16_f32 v229, v230, v231
	v_cvt_pk_bf16_f32 v230, v236, v237
	v_cvt_pk_bf16_f32 v231, v240, v241
	ds_write_b128 v178, v[228:231]
	v_cvt_pk_bf16_f32 v228, v232, v233
	v_cvt_pk_bf16_f32 v229, v234, v235
	v_cvt_pk_bf16_f32 v230, v238, v239
	v_cvt_pk_bf16_f32 v231, v242, v243
	ds_write_b128 v179, v[228:231]
	s_waitcnt vmcnt(7)
	v_and_b32_e32 v231, 0xffff0000, v16
	v_lshlrev_b32_e32 v230, 16, v16
	v_and_b32_e32 v229, 0xffff0000, v12
	v_lshlrev_b32_e32 v228, 16, v12
	v_pk_mul_f32 v[232:233], v[102:103], v[230:231]
	v_and_b32_e32 v231, 0xffff0000, v13
	v_lshlrev_b32_e32 v230, 16, v13
	v_and_b32_e32 v237, 0xffff0000, v14
	v_lshlrev_b32_e32 v236, 16, v14
	v_and_b32_e32 v241, 0xffff0000, v15
	v_lshlrev_b32_e32 v240, 16, v15
	v_pk_mul_f32 v[228:229], v[100:101], v[228:229]
	v_pk_mul_f32 v[230:231], v[100:101], v[230:231]
	v_and_b32_e32 v235, 0xffff0000, v17
	v_lshlrev_b32_e32 v234, 16, v17
	v_pk_mul_f32 v[236:237], v[100:101], v[236:237]
	v_and_b32_e32 v239, 0xffff0000, v18
	v_lshlrev_b32_e32 v238, 16, v18
	v_pk_mul_f32 v[240:241], v[100:101], v[240:241]
	v_and_b32_e32 v243, 0xffff0000, v19
	v_lshlrev_b32_e32 v242, 16, v19
	global_load_dwordx4 v[12:15], v88, s[38:39]
	global_load_dwordx4 v[16:19], v88, s[54:55]
	v_pk_mul_f32 v[234:235], v[102:103], v[234:235]
	v_pk_mul_f32 v[238:239], v[102:103], v[238:239]
	v_pk_mul_f32 v[242:243], v[102:103], v[242:243]
	v_cvt_pk_bf16_f32 v228, v228, v229
	v_cvt_pk_bf16_f32 v229, v230, v231
	v_cvt_pk_bf16_f32 v230, v236, v237
	v_cvt_pk_bf16_f32 v231, v240, v241
	ds_write_b128 v180, v[228:231]
	v_cvt_pk_bf16_f32 v228, v232, v233
	v_cvt_pk_bf16_f32 v229, v234, v235
	v_cvt_pk_bf16_f32 v230, v238, v239
	v_cvt_pk_bf16_f32 v231, v242, v243
	ds_write_b128 v181, v[228:231]
	s_waitcnt vmcnt(7)
	v_and_b32_e32 v231, 0xffff0000, v24
	v_lshlrev_b32_e32 v230, 16, v24
	v_and_b32_e32 v229, 0xffff0000, v20
	v_lshlrev_b32_e32 v228, 16, v20
	v_pk_mul_f32 v[232:233], v[102:103], v[230:231]
	v_and_b32_e32 v231, 0xffff0000, v21
	v_lshlrev_b32_e32 v230, 16, v21
	v_and_b32_e32 v237, 0xffff0000, v22
	v_lshlrev_b32_e32 v236, 16, v22
	v_and_b32_e32 v241, 0xffff0000, v23
	v_lshlrev_b32_e32 v240, 16, v23
	v_pk_mul_f32 v[228:229], v[100:101], v[228:229]
	v_pk_mul_f32 v[230:231], v[100:101], v[230:231]
	v_and_b32_e32 v235, 0xffff0000, v25
	v_lshlrev_b32_e32 v234, 16, v25
	v_pk_mul_f32 v[236:237], v[100:101], v[236:237]
	v_and_b32_e32 v239, 0xffff0000, v26
	v_lshlrev_b32_e32 v238, 16, v26
	v_pk_mul_f32 v[240:241], v[100:101], v[240:241]
	v_and_b32_e32 v243, 0xffff0000, v27
	v_lshlrev_b32_e32 v242, 16, v27
	global_load_dwordx4 v[20:23], v90, s[38:39]
	global_load_dwordx4 v[24:27], v90, s[54:55]
	v_pk_mul_f32 v[234:235], v[102:103], v[234:235]
	v_pk_mul_f32 v[238:239], v[102:103], v[238:239]
	v_pk_mul_f32 v[242:243], v[102:103], v[242:243]
	v_cvt_pk_bf16_f32 v228, v228, v229
	v_cvt_pk_bf16_f32 v229, v230, v231
	v_cvt_pk_bf16_f32 v230, v236, v237
	v_cvt_pk_bf16_f32 v231, v240, v241
	ds_write_b128 v182, v[228:231]
	v_cvt_pk_bf16_f32 v228, v232, v233
	v_cvt_pk_bf16_f32 v229, v234, v235
	v_cvt_pk_bf16_f32 v230, v238, v239
	v_cvt_pk_bf16_f32 v231, v242, v243
	ds_write_b128 v183, v[228:231]
	s_waitcnt vmcnt(7)
	v_and_b32_e32 v231, 0xffff0000, v32
	v_lshlrev_b32_e32 v230, 16, v32
	v_and_b32_e32 v229, 0xffff0000, v28
	v_lshlrev_b32_e32 v228, 16, v28
	v_pk_mul_f32 v[232:233], v[102:103], v[230:231]
	v_and_b32_e32 v231, 0xffff0000, v29
	v_lshlrev_b32_e32 v230, 16, v29
	v_and_b32_e32 v237, 0xffff0000, v30
	v_lshlrev_b32_e32 v236, 16, v30
	v_and_b32_e32 v241, 0xffff0000, v31
	v_lshlrev_b32_e32 v240, 16, v31
	v_pk_mul_f32 v[228:229], v[100:101], v[228:229]
	v_pk_mul_f32 v[230:231], v[100:101], v[230:231]
	v_and_b32_e32 v235, 0xffff0000, v33
	v_lshlrev_b32_e32 v234, 16, v33
	v_pk_mul_f32 v[236:237], v[100:101], v[236:237]
	v_and_b32_e32 v239, 0xffff0000, v34
	v_lshlrev_b32_e32 v238, 16, v34
	v_pk_mul_f32 v[240:241], v[100:101], v[240:241]
	v_and_b32_e32 v243, 0xffff0000, v35
	v_lshlrev_b32_e32 v242, 16, v35
	global_load_dwordx4 v[28:31], v92, s[38:39]
	global_load_dwordx4 v[32:35], v92, s[54:55]
	v_pk_mul_f32 v[234:235], v[102:103], v[234:235]
	v_pk_mul_f32 v[238:239], v[102:103], v[238:239]
	v_pk_mul_f32 v[242:243], v[102:103], v[242:243]
	v_cvt_pk_bf16_f32 v228, v228, v229
	v_cvt_pk_bf16_f32 v229, v230, v231
	v_cvt_pk_bf16_f32 v230, v236, v237
	v_cvt_pk_bf16_f32 v231, v240, v241
	ds_write_b128 v184, v[228:231]
	v_cvt_pk_bf16_f32 v228, v232, v233
	v_cvt_pk_bf16_f32 v229, v234, v235
	v_cvt_pk_bf16_f32 v230, v238, v239
	v_cvt_pk_bf16_f32 v231, v242, v243
	ds_write_b128 v185, v[228:231]
	s_and_saveexec_b64 s[40:41], vcc
	ds_write_b32 v171, v173
	s_or_b64 exec, exec, s[40:41]
	s_add_i32 s36, s45, 1
	s_cmpk_eq_i32 s42, 0xffbd
	s_waitcnt vmcnt(8)
	ds_write_b128 v172, v[212:215]
	s_branch .LBB0_70
